# P7 K-loop: per-cluster s_setprio flips removed; one static s_setprio 1 for the younger wave-half (wr==1) at loop entry, s_setprio 0 at loop exit
# baseline (speedup 1.0000x reference)
;     __device__ bool next(int i, Unit& u) const { return at((long)i * G + c, u); }
;     __device__ bool next(int i, Unit& u) const { if (i > 0) return false; u.pm = pm; u.pn = pn; u.g = 0; u.nt = nt; u.k0 = 0; u.part = -1; return true; }
; #define PG8_STAGE(bufoff, gbase, voff) do { _Pragma("unroll") for (int _i = 0; _i < 2; ++_i) \
;         __builtin_amdgcn_global_load_lds((const unsigned*)((const char*)(gbase) + (voff)[_i]), (LAS unsigned*)(lds + (bufoff) + ldsw + _i * 8192), 16, 0, 0); } while (0)
; #define PG8_LDA(dst, b, h) do { _Pragma("unroll") for (int m = 0; m < 4; ++m) _Pragma("unroll") for (int k = 0; k < 2; ++k) dst[m][k] = *(const LAS bf16x8*)(lds + PG8_SA(b, h) + aoff + m * 2048 + k * 1024); } while (0)
; #define PG8_LDB(dst, b, h) do { _Pragma("unroll") for (int n = 0; n < 2; ++n) _Pragma("unroll") for (int k = 0; k < 2; ++k) dst[n][k] = *(const LAS bf16x8*)(lds + PG8_SB(b, h) + boff + n * 2048 + k * 1024); } while (0)
; #define PG8_WAIT_V(n) asm volatile("s_waitcnt vmcnt(" #n ")" ::: "memory")
; #define PG8_BAR __builtin_amdgcn_s_barrier()
; template <class Epi, class Sched>
; __device__ __forceinline__ void gemm_phase(LAS unsigned char* lds, const Gemm g, const Sched& S, const Epi& E) {
;     ...
;         const bool has_next = S.next(ui + 1, nxt);
;         const char* nA = has_next ? PG8_ABASE(nxt) : cA; const char* nB = has_next ? PG8_BBASE(nxt) : cB;
;         const int nt = cur.nt;
;         for (int t = 0; t < nt; t += 2) {
;             const bool last = (t == nt - 2);
;             const char* a1 = cA + (size_t)(t + 1) * kstep;
;             const char* a2 = last ? nA : cA + (size_t)(t + 2) * kstep; const char* b2 = last ? nB : cB + (size_t)(t + 2) * kstep;
;             const char* a3 = a2 + kstep; const char* b3 = b2 + kstep;
;             PG8_LDB(B0, 0, 0); PG8_LDB(B1, 0, 1); PG8_SCHED; PG8_LDA(At, 0, 0); PG8_STAGE(PG8_SA(1, 1), a1 + hstepA, voffA);
;             PG8_WAIT_V(8); PG8_WAIT_L(0); PG8_BAR; PG8_MMA(0, 0, At, B0); PG8_MMA(0, 1, At, B1); PG8_BAR; PG8_SCHED;
;     ...
; #pragma unroll
;         for (int a = 0; a < 2; ++a)
; #pragma unroll
;             for (int b = 0; b < 2; ++b)
; #pragma unroll
;                 for (int m = 0; m < 4; ++m)
; #pragma unroll
;                     for (int n = 0; n < 2; ++n) acc[a][b][m][n] = (f32x4){0.f, 0.f, 0.f, 0.f};
;         cur = nxt; cA = nA; cB = nB; ++ui;
;         if (wr == 1) PG8_BAR;
.LBB0_836:
	s_ashr_i32 s19, s18, 31
	s_lshl_b64 s[20:21], s[18:19], 20
	s_add_u32 s20, s14, s20
	s_addc_u32 s21, s15, s21
	s_and_b64 s[22:23], s[0:1], exec
	s_cselect_b32 s19, s21, s37
	s_cselect_b32 s51, s20, s36
	s_ashr_i32 s17, s16, 31
	s_lshl_b64 s[22:23], s[16:17], 20
	s_add_u32 s22, s88, s22
	s_addc_u32 s23, s89, s23
	s_and_b64 s[40:41], s[0:1], exec
	s_cselect_b32 s17, s23, s39
	s_cselect_b32 s52, s22, s38
	s_add_u32 s36, s36, 0x80800
	s_addc_u32 s37, s37, 0
	s_add_u32 s53, s38, 0x100
	v_mov_b32_e32 v0, 0
	s_addc_u32 s54, s39, 0
	s_mov_b32 s55, -2
	v_mov_b32_e32 v1, v0
	v_mov_b32_e32 v2, v0
	v_mov_b32_e32 v3, v0
	v_mov_b32_e32 v4, v0
	v_mov_b32_e32 v5, v0
	v_mov_b32_e32 v6, v0
	v_mov_b32_e32 v7, v0
	v_mov_b32_e32 v16, v0
	v_mov_b32_e32 v17, v0
	v_mov_b32_e32 v18, v0
	v_mov_b32_e32 v19, v0
	v_mov_b32_e32 v20, v0
	v_mov_b32_e32 v21, v0
	v_mov_b32_e32 v22, v0
	v_mov_b32_e32 v23, v0
	s_waitcnt vmcnt(0)
	v_mov_b32_e32 v32, v0
	v_mov_b32_e32 v33, v0
	v_mov_b32_e32 v34, v0
	v_mov_b32_e32 v35, v0
	v_mov_b32_e32 v36, v0
	v_mov_b32_e32 v37, v0
	v_mov_b32_e32 v38, v0
	v_mov_b32_e32 v39, v0
	v_mov_b32_e32 v48, v0
	v_mov_b32_e32 v49, v0
	v_mov_b32_e32 v50, v0
	v_mov_b32_e32 v51, v0
	v_mov_b32_e32 v52, v0
	v_mov_b32_e32 v53, v0
	v_mov_b32_e32 v54, v0
	v_mov_b32_e32 v55, v0
	v_mov_b32_e32 v8, v0
	v_mov_b32_e32 v9, v0
	v_mov_b32_e32 v10, v0
	v_mov_b32_e32 v11, v0
	v_mov_b32_e32 v12, v0
	v_mov_b32_e32 v13, v0
	v_mov_b32_e32 v14, v0
	v_mov_b32_e32 v15, v0
	v_mov_b32_e32 v24, v0
	v_mov_b32_e32 v25, v0
	v_mov_b32_e32 v26, v0
	v_mov_b32_e32 v27, v0
	v_mov_b32_e32 v28, v0
	v_mov_b32_e32 v29, v0
	v_mov_b32_e32 v30, v0
	v_mov_b32_e32 v31, v0
	v_mov_b32_e32 v40, v0
	v_mov_b32_e32 v41, v0
	v_mov_b32_e32 v42, v0
	v_mov_b32_e32 v43, v0
	v_mov_b32_e32 v44, v0
	v_mov_b32_e32 v45, v0
	v_mov_b32_e32 v46, v0
	v_mov_b32_e32 v47, v0
	v_mov_b32_e32 v56, v0
	v_mov_b32_e32 v57, v0
	v_mov_b32_e32 v58, v0
	v_mov_b32_e32 v59, v0
	v_mov_b32_e32 v60, v0
	v_mov_b32_e32 v61, v0
	v_mov_b32_e32 v62, v0
	v_mov_b32_e32 v63, v0
	v_mov_b32_e32 v64, v0
	v_mov_b32_e32 v65, v0
	v_mov_b32_e32 v66, v0
	v_mov_b32_e32 v67, v0
	v_mov_b32_e32 v68, v0
	v_mov_b32_e32 v69, v0
	v_mov_b32_e32 v70, v0
	v_mov_b32_e32 v71, v0
	v_mov_b32_e32 v80, v0
	v_mov_b32_e32 v81, v0
	v_mov_b32_e32 v82, v0
	v_mov_b32_e32 v83, v0
	v_mov_b32_e32 v84, v0
	v_mov_b32_e32 v85, v0
	v_mov_b32_e32 v86, v0
	v_mov_b32_e32 v87, v0
	v_mov_b32_e32 v96, v0
	v_mov_b32_e32 v97, v0
	v_mov_b32_e32 v98, v0
	v_mov_b32_e32 v99, v0
	v_mov_b32_e32 v100, v0
	v_mov_b32_e32 v101, v0
	v_mov_b32_e32 v102, v0
	v_mov_b32_e32 v103, v0
	v_mov_b32_e32 v112, v0
	v_mov_b32_e32 v113, v0
	v_mov_b32_e32 v114, v0
	v_mov_b32_e32 v115, v0
	v_mov_b32_e32 v116, v0
	v_mov_b32_e32 v117, v0
	v_mov_b32_e32 v118, v0
	v_mov_b32_e32 v119, v0
	v_mov_b32_e32 v72, v0
	v_mov_b32_e32 v73, v0
	v_mov_b32_e32 v74, v0
	v_mov_b32_e32 v75, v0
	v_mov_b32_e32 v76, v0
	v_mov_b32_e32 v77, v0
	v_mov_b32_e32 v78, v0
	v_mov_b32_e32 v79, v0
	v_mov_b32_e32 v88, v0
	v_mov_b32_e32 v89, v0
	v_mov_b32_e32 v90, v0
	v_mov_b32_e32 v91, v0
	v_mov_b32_e32 v92, v0
	v_mov_b32_e32 v93, v0
	v_mov_b32_e32 v94, v0
	v_mov_b32_e32 v95, v0
	v_mov_b32_e32 v104, v0
	v_mov_b32_e32 v105, v0
	v_mov_b32_e32 v106, v0
	v_mov_b32_e32 v107, v0
	v_mov_b32_e32 v108, v0
	v_mov_b32_e32 v109, v0
	v_mov_b32_e32 v110, v0
	v_mov_b32_e32 v111, v0
	v_mov_b32_e32 v120, v0
	v_mov_b32_e32 v121, v0
	v_mov_b32_e32 v122, v0
	v_mov_b32_e32 v123, v0
	v_mov_b32_e32 v124, v0
	v_mov_b32_e32 v125, v0
	v_mov_b32_e32 v126, v0
	v_mov_b32_e32 v127, v0
	s_cmp_lg_u64 s[8:9], 0
	s_cbranch_scc0 .Ledge_p7
	s_barrier
	s_setprio 1
.Ledge_p7:
.LBB0_837:
	ds_read_b128 v[146:149], v155
	ds_read_b128 v[160:163], v155 offset:1024
	ds_read_b128 v[164:167], v155 offset:2048
	ds_read_b128 v[168:171], v155 offset:3072
	ds_read_b128 v[172:175], v156
	ds_read_b128 v[176:179], v156 offset:1024
	ds_read_b128 v[180:183], v156 offset:2048
	ds_read_b128 v[184:187], v156 offset:3072
	s_add_u32 s38, s36, 0xfff80800
	s_addc_u32 s39, s37, -1
	s_cmp_eq_u32 s55, 28
	s_cselect_b32 s41, s19, s39
	s_cselect_b32 s40, s51, s38
	s_cselect_b32 s39, s17, s54
	s_cselect_b32 s38, s52, s53
	v_lshl_add_u64 v[150:151], s[36:37], 0, v[138:139]
	s_add_i32 m0, s25, 0xc000
	ds_read_b128 v[188:191], v157
	ds_read_b128 v[192:195], v157 offset:1024
	ds_read_b128 v[196:199], v157 offset:2048
	ds_read_b128 v[200:203], v157 offset:3072
	ds_read_b128 v[204:207], v157 offset:4096
	ds_read_b128 v[208:211], v157 offset:5120
	ds_read_b128 v[212:215], v157 offset:6144
	ds_read_b128 v[216:219], v157 offset:7168
	global_load_lds_dwordx4 v[150:151], off
	v_lshl_add_u64 v[150:151], s[36:37], 0, v[140:141]
	s_add_i32 m0, s25, 0xe000
	s_nop 0
	global_load_lds_dwordx4 v[150:151], off
	s_waitcnt vmcnt(8)
	s_waitcnt lgkmcnt(0)
	s_barrier
; #define PG8_STAGE(bufoff, gbase, voff) do { _Pragma("unroll") for (int _i = 0; _i < 2; ++_i) \
;         __builtin_amdgcn_global_load_lds((const unsigned*)((const char*)(gbase) + (voff)[_i]), (LAS unsigned*)(lds + (bufoff) + ldsw + _i * 8192), 16, 0, 0); } while (0)
; #define PG8_LDA(dst, b, h) do { _Pragma("unroll") for (int m = 0; m < 4; ++m) _Pragma("unroll") for (int k = 0; k < 2; ++k) dst[m][k] = *(const LAS bf16x8*)(lds + PG8_SA(b, h) + aoff + m * 2048 + k * 1024); } while (0)
; #define PG8_MMA(ai, bj, At, Bt) do { __builtin_amdgcn_s_setprio(1); _Pragma("unroll") for (int m = 0; m < 4; ++m) _Pragma("unroll") for (int n = 0; n < 2; ++n) _Pragma("unroll") for (int k = 0; k < 2; ++k) \
;         acc[ai][bj][m][n] = __builtin_amdgcn_mfma_f32_16x16x32_bf16(Bt[n][k], At[m][k], acc[ai][bj][m][n], 0, 0, 0); __builtin_amdgcn_s_setprio(0); } while (0)
; #define PG8_WAIT_V(n) asm volatile("s_waitcnt vmcnt(" #n ")" ::: "memory")
; #define PG8_WAIT_L(n) asm volatile("s_waitcnt lgkmcnt(" #n ")" ::: "memory")
; #define PG8_BAR __builtin_amdgcn_s_barrier()
; #define PG8_SCHED __builtin_amdgcn_sched_barrier(0)
; template <class Epi, class Sched>
; __device__ __forceinline__ void gemm_phase(LAS unsigned char* lds, const Gemm g, const Sched& S, const Epi& E) {
;     ...
;             PG8_WAIT_V(8); PG8_WAIT_L(0); PG8_BAR; PG8_MMA(0, 0, At, B0); PG8_MMA(0, 1, At, B1); PG8_BAR; PG8_SCHED;
;             PG8_LDA(At, 0, 1); PG8_STAGE(PG8_SB(0, 0), b2, voffB); PG8_STAGE(PG8_SB(0, 1), b2 + hstepB, voffB); PG8_STAGE(PG8_SA(0, 0), a2, voffA);
;             PG8_WAIT_V(8); PG8_WAIT_L(0); PG8_BAR; PG8_MMA(1, 0, At, B0); PG8_MMA(1, 1, At, B1); PG8_BAR; PG8_SCHED;
	s_waitcnt lgkmcnt(0)
	v_mfma_f32_16x16x32_bf16 v[124:127], v[146:149], v[188:191], v[124:127]
	v_mfma_f32_16x16x32_bf16 v[120:123], v[164:167], v[188:191], v[120:123]
	v_mfma_f32_16x16x32_bf16 v[108:111], v[146:149], v[196:199], v[108:111]
	v_mfma_f32_16x16x32_bf16 v[104:107], v[164:167], v[196:199], v[104:107]
	v_mfma_f32_16x16x32_bf16 v[92:95], v[146:149], v[204:207], v[92:95]
	v_mfma_f32_16x16x32_bf16 v[88:91], v[164:167], v[204:207], v[88:91]
	v_mfma_f32_16x16x32_bf16 v[76:79], v[146:149], v[212:215], v[76:79]
	v_mfma_f32_16x16x32_bf16 v[72:75], v[164:167], v[212:215], v[72:75]
	v_mfma_f32_16x16x32_bf16 v[124:127], v[160:163], v[192:195], v[124:127]
	v_mfma_f32_16x16x32_bf16 v[120:123], v[168:171], v[192:195], v[120:123]
	v_mfma_f32_16x16x32_bf16 v[108:111], v[160:163], v[200:203], v[108:111]
	v_mfma_f32_16x16x32_bf16 v[104:107], v[168:171], v[200:203], v[104:107]
	v_mfma_f32_16x16x32_bf16 v[92:95], v[160:163], v[208:211], v[92:95]
	v_mfma_f32_16x16x32_bf16 v[88:91], v[168:171], v[208:211], v[88:91]
	v_mfma_f32_16x16x32_bf16 v[76:79], v[160:163], v[216:219], v[76:79]
	v_mfma_f32_16x16x32_bf16 v[72:75], v[168:171], v[216:219], v[72:75]
	v_mfma_f32_16x16x32_bf16 v[116:119], v[172:175], v[188:191], v[116:119]
	v_mfma_f32_16x16x32_bf16 v[112:115], v[180:183], v[188:191], v[112:115]
	v_mfma_f32_16x16x32_bf16 v[100:103], v[172:175], v[196:199], v[100:103]
	v_mfma_f32_16x16x32_bf16 v[96:99], v[180:183], v[196:199], v[96:99]
	v_mfma_f32_16x16x32_bf16 v[84:87], v[172:175], v[204:207], v[84:87]
	v_mfma_f32_16x16x32_bf16 v[80:83], v[180:183], v[204:207], v[80:83]
	v_mfma_f32_16x16x32_bf16 v[68:71], v[172:175], v[212:215], v[68:71]
	v_mfma_f32_16x16x32_bf16 v[64:67], v[180:183], v[212:215], v[64:67]
	v_mfma_f32_16x16x32_bf16 v[116:119], v[176:179], v[192:195], v[116:119]
	v_mfma_f32_16x16x32_bf16 v[112:115], v[184:187], v[192:195], v[112:115]
	v_mfma_f32_16x16x32_bf16 v[100:103], v[176:179], v[200:203], v[100:103]
	v_mfma_f32_16x16x32_bf16 v[96:99], v[184:187], v[200:203], v[96:99]
	v_mfma_f32_16x16x32_bf16 v[84:87], v[176:179], v[208:211], v[84:87]
	v_mfma_f32_16x16x32_bf16 v[80:83], v[184:187], v[208:211], v[80:83]
	v_mfma_f32_16x16x32_bf16 v[68:71], v[176:179], v[216:219], v[68:71]
	v_mfma_f32_16x16x32_bf16 v[64:67], v[184:187], v[216:219], v[64:67]
	s_barrier
	s_add_i32 s48, s46, s5
	v_lshl_add_u64 v[150:151], s[38:39], 0, v[130:131]
	s_mov_b32 m0, s48
	ds_read_b128 v[188:191], v157 offset:16384
	ds_read_b128 v[192:195], v157 offset:17408
	ds_read_b128 v[196:199], v157 offset:18432
	ds_read_b128 v[200:203], v157 offset:19456
	ds_read_b128 v[204:207], v157 offset:20480
	ds_read_b128 v[208:211], v157 offset:21504
	ds_read_b128 v[212:215], v157 offset:22528
	ds_read_b128 v[216:219], v157 offset:23552
	global_load_lds_dwordx4 v[150:151], off
	s_add_i32 m0, s48, 0x2000
	s_add_u32 s48, s38, 0x80000
	v_lshl_add_u64 v[220:221], s[38:39], 0, v[134:135]
	s_addc_u32 s49, s39, 0
	s_add_i32 s56, s47, s5
	global_load_lds_dwordx4 v[220:221], off
	v_lshl_add_u64 v[222:223], s[48:49], 0, v[130:131]
	s_mov_b32 m0, s56
	v_lshl_add_u64 v[224:225], s[40:41], 0, v[132:133]
	global_load_lds_dwordx4 v[222:223], off
	v_lshl_add_u64 v[222:223], s[48:49], 0, v[134:135]
	s_add_i32 m0, s56, 0x2000
	s_nop 0
	global_load_lds_dwordx4 v[222:223], off
	v_lshl_add_u64 v[222:223], s[40:41], 0, v[128:129]
	s_mov_b32 m0, s25
	s_nop 0
	global_load_lds_dwordx4 v[222:223], off
	s_mov_b32 m0, s33
	s_nop 0
	global_load_lds_dwordx4 v[224:225], off
	s_waitcnt vmcnt(8)
	s_waitcnt lgkmcnt(0)
	s_barrier
	s_waitcnt lgkmcnt(0)
	v_mfma_f32_16x16x32_bf16 v[60:63], v[146:149], v[188:191], v[60:63]
	v_mfma_f32_16x16x32_bf16 v[56:59], v[164:167], v[188:191], v[56:59]
	v_mfma_f32_16x16x32_bf16 v[44:47], v[146:149], v[196:199], v[44:47]
	v_mfma_f32_16x16x32_bf16 v[40:43], v[164:167], v[196:199], v[40:43]
	v_mfma_f32_16x16x32_bf16 v[28:31], v[146:149], v[204:207], v[28:31]
	v_mfma_f32_16x16x32_bf16 v[24:27], v[164:167], v[204:207], v[24:27]
	v_mfma_f32_16x16x32_bf16 v[12:15], v[146:149], v[212:215], v[12:15]
	v_mfma_f32_16x16x32_bf16 v[8:11], v[164:167], v[212:215], v[8:11]
	v_mfma_f32_16x16x32_bf16 v[60:63], v[160:163], v[192:195], v[60:63]
	v_mfma_f32_16x16x32_bf16 v[56:59], v[168:171], v[192:195], v[56:59]
	v_mfma_f32_16x16x32_bf16 v[44:47], v[160:163], v[200:203], v[44:47]
	v_mfma_f32_16x16x32_bf16 v[40:43], v[168:171], v[200:203], v[40:43]
	v_mfma_f32_16x16x32_bf16 v[28:31], v[160:163], v[208:211], v[28:31]
	v_mfma_f32_16x16x32_bf16 v[24:27], v[168:171], v[208:211], v[24:27]
	v_mfma_f32_16x16x32_bf16 v[12:15], v[160:163], v[216:219], v[12:15]
	v_mfma_f32_16x16x32_bf16 v[8:11], v[168:171], v[216:219], v[8:11]
	v_mfma_f32_16x16x32_bf16 v[52:55], v[172:175], v[188:191], v[52:55]
	v_mfma_f32_16x16x32_bf16 v[48:51], v[180:183], v[188:191], v[48:51]
	v_mfma_f32_16x16x32_bf16 v[36:39], v[172:175], v[196:199], v[36:39]
	v_mfma_f32_16x16x32_bf16 v[32:35], v[180:183], v[196:199], v[32:35]
	v_mfma_f32_16x16x32_bf16 v[20:23], v[172:175], v[204:207], v[20:23]
	v_mfma_f32_16x16x32_bf16 v[16:19], v[180:183], v[204:207], v[16:19]
	v_mfma_f32_16x16x32_bf16 v[4:7], v[172:175], v[212:215], v[4:7]
	v_mfma_f32_16x16x32_bf16 v[0:3], v[180:183], v[212:215], v[0:3]
	v_mfma_f32_16x16x32_bf16 v[52:55], v[176:179], v[192:195], v[52:55]
	v_mfma_f32_16x16x32_bf16 v[48:51], v[184:187], v[192:195], v[48:51]
	v_mfma_f32_16x16x32_bf16 v[36:39], v[176:179], v[200:203], v[36:39]
	v_mfma_f32_16x16x32_bf16 v[32:35], v[184:187], v[200:203], v[32:35]
	v_mfma_f32_16x16x32_bf16 v[20:23], v[176:179], v[208:211], v[20:23]
	v_mfma_f32_16x16x32_bf16 v[16:19], v[184:187], v[208:211], v[16:19]
	v_mfma_f32_16x16x32_bf16 v[4:7], v[176:179], v[216:219], v[4:7]
	v_mfma_f32_16x16x32_bf16 v[0:3], v[184:187], v[216:219], v[0:3]
	s_barrier
; #define PG8_STAGE(bufoff, gbase, voff) do { _Pragma("unroll") for (int _i = 0; _i < 2; ++_i) \
;         __builtin_amdgcn_global_load_lds((const unsigned*)((const char*)(gbase) + (voff)[_i]), (LAS unsigned*)(lds + (bufoff) + ldsw + _i * 8192), 16, 0, 0); } while (0)
; #define PG8_LDA(dst, b, h) do { _Pragma("unroll") for (int m = 0; m < 4; ++m) _Pragma("unroll") for (int k = 0; k < 2; ++k) dst[m][k] = *(const LAS bf16x8*)(lds + PG8_SA(b, h) + aoff + m * 2048 + k * 1024); } while (0)
; #define PG8_LDB(dst, b, h) do { _Pragma("unroll") for (int n = 0; n < 2; ++n) _Pragma("unroll") for (int k = 0; k < 2; ++k) dst[n][k] = *(const LAS bf16x8*)(lds + PG8_SB(b, h) + boff + n * 2048 + k * 1024); } while (0)
; #define PG8_MMA(ai, bj, At, Bt) do { __builtin_amdgcn_s_setprio(1); _Pragma("unroll") for (int m = 0; m < 4; ++m) _Pragma("unroll") for (int n = 0; n < 2; ++n) _Pragma("unroll") for (int k = 0; k < 2; ++k) \
;         acc[ai][bj][m][n] = __builtin_amdgcn_mfma_f32_16x16x32_bf16(Bt[n][k], At[m][k], acc[ai][bj][m][n], 0, 0, 0); __builtin_amdgcn_s_setprio(0); } while (0)
; #define PG8_WAIT_V(n) asm volatile("s_waitcnt vmcnt(" #n ")" ::: "memory")
; #define PG8_WAIT_L(n) asm volatile("s_waitcnt lgkmcnt(" #n ")" ::: "memory")
; #define PG8_BAR __builtin_amdgcn_s_barrier()
; #define PG8_SCHED __builtin_amdgcn_sched_barrier(0)
; template <class Epi, class Sched>
; __device__ __forceinline__ void gemm_phase(LAS unsigned char* lds, const Gemm g, const Sched& S, const Epi& E) {
;     ...
;             PG8_LDB(B0, 1, 0); PG8_LDB(B1, 1, 1); PG8_SCHED; PG8_LDA(At, 1, 0); PG8_STAGE(PG8_SA(0, 1), a2 + hstepA, voffA);
;             PG8_WAIT_V(8); PG8_WAIT_L(0); PG8_BAR; PG8_MMA(0, 0, At, B0); PG8_MMA(0, 1, At, B1); PG8_BAR; PG8_SCHED;
	s_add_i32 s48, 0, 0x18000
	v_add_u32_e32 v159, s48, v153
	s_add_i32 s49, 0, 0x1c000
	ds_read_b128 v[146:149], v159
	ds_read_b128 v[160:163], v159 offset:1024
	ds_read_b128 v[164:167], v159 offset:2048
	ds_read_b128 v[168:171], v159 offset:3072
	v_add_u32_e32 v159, s49, v153
	ds_read_b128 v[172:175], v159
	ds_read_b128 v[176:179], v159 offset:1024
	ds_read_b128 v[180:183], v159 offset:2048
	ds_read_b128 v[184:187], v159 offset:3072
	s_add_u32 s40, s40, 0x80000
	s_addc_u32 s41, s41, 0
	s_mov_b32 m0, s34
	v_lshl_add_u64 v[226:227], s[40:41], 0, v[128:129]
	ds_read_b128 v[188:191], v157 offset:32768
	ds_read_b128 v[192:195], v157 offset:33792
	ds_read_b128 v[196:199], v157 offset:34816
	ds_read_b128 v[200:203], v157 offset:35840
	ds_read_b128 v[204:207], v157 offset:36864
	ds_read_b128 v[208:211], v157 offset:37888
	ds_read_b128 v[212:215], v157 offset:38912
	ds_read_b128 v[216:219], v157 offset:39936
	global_load_lds_dwordx4 v[226:227], off
	v_lshl_add_u64 v[226:227], s[40:41], 0, v[132:133]
	s_mov_b32 m0, s35
	s_nop 0
	global_load_lds_dwordx4 v[226:227], off
	s_waitcnt vmcnt(8)
	s_waitcnt lgkmcnt(0)
	s_barrier
	s_waitcnt lgkmcnt(0)
	v_mfma_f32_16x16x32_bf16 v[124:127], v[146:149], v[188:191], v[124:127]
	v_mfma_f32_16x16x32_bf16 v[120:123], v[164:167], v[188:191], v[120:123]
	v_mfma_f32_16x16x32_bf16 v[108:111], v[146:149], v[196:199], v[108:111]
	v_mfma_f32_16x16x32_bf16 v[104:107], v[164:167], v[196:199], v[104:107]
	v_mfma_f32_16x16x32_bf16 v[92:95], v[146:149], v[204:207], v[92:95]
	v_mfma_f32_16x16x32_bf16 v[88:91], v[164:167], v[204:207], v[88:91]
	v_mfma_f32_16x16x32_bf16 v[76:79], v[146:149], v[212:215], v[76:79]
	v_mfma_f32_16x16x32_bf16 v[72:75], v[164:167], v[212:215], v[72:75]
	v_mfma_f32_16x16x32_bf16 v[124:127], v[160:163], v[192:195], v[124:127]
	v_mfma_f32_16x16x32_bf16 v[120:123], v[168:171], v[192:195], v[120:123]
	v_mfma_f32_16x16x32_bf16 v[108:111], v[160:163], v[200:203], v[108:111]
	v_mfma_f32_16x16x32_bf16 v[104:107], v[168:171], v[200:203], v[104:107]
	v_mfma_f32_16x16x32_bf16 v[92:95], v[160:163], v[208:211], v[92:95]
	v_mfma_f32_16x16x32_bf16 v[88:91], v[168:171], v[208:211], v[88:91]
	v_mfma_f32_16x16x32_bf16 v[76:79], v[160:163], v[216:219], v[76:79]
	v_mfma_f32_16x16x32_bf16 v[72:75], v[168:171], v[216:219], v[72:75]
	v_mfma_f32_16x16x32_bf16 v[116:119], v[172:175], v[188:191], v[116:119]
	v_mfma_f32_16x16x32_bf16 v[112:115], v[180:183], v[188:191], v[112:115]
	v_mfma_f32_16x16x32_bf16 v[100:103], v[172:175], v[196:199], v[100:103]
	v_mfma_f32_16x16x32_bf16 v[96:99], v[180:183], v[196:199], v[96:99]
	v_mfma_f32_16x16x32_bf16 v[84:87], v[172:175], v[204:207], v[84:87]
	v_mfma_f32_16x16x32_bf16 v[80:83], v[180:183], v[204:207], v[80:83]
	v_mfma_f32_16x16x32_bf16 v[68:71], v[172:175], v[212:215], v[68:71]
	v_mfma_f32_16x16x32_bf16 v[64:67], v[180:183], v[212:215], v[64:67]
	v_mfma_f32_16x16x32_bf16 v[116:119], v[176:179], v[192:195], v[116:119]
	v_mfma_f32_16x16x32_bf16 v[112:115], v[184:187], v[192:195], v[112:115]
	v_mfma_f32_16x16x32_bf16 v[100:103], v[176:179], v[200:203], v[100:103]
	v_mfma_f32_16x16x32_bf16 v[96:99], v[184:187], v[200:203], v[96:99]
	v_mfma_f32_16x16x32_bf16 v[84:87], v[176:179], v[208:211], v[84:87]
	v_mfma_f32_16x16x32_bf16 v[80:83], v[184:187], v[208:211], v[80:83]
	v_mfma_f32_16x16x32_bf16 v[68:71], v[176:179], v[216:219], v[68:71]
	v_mfma_f32_16x16x32_bf16 v[64:67], v[184:187], v[216:219], v[64:67]
	s_barrier
; #define PG8_STAGE(bufoff, gbase, voff) do { _Pragma("unroll") for (int _i = 0; _i < 2; ++_i) \
;         __builtin_amdgcn_global_load_lds((const unsigned*)((const char*)(gbase) + (voff)[_i]), (LAS unsigned*)(lds + (bufoff) + ldsw + _i * 8192), 16, 0, 0); } while (0)
; #define PG8_LDA(dst, b, h) do { _Pragma("unroll") for (int m = 0; m < 4; ++m) _Pragma("unroll") for (int k = 0; k < 2; ++k) dst[m][k] = *(const LAS bf16x8*)(lds + PG8_SA(b, h) + aoff + m * 2048 + k * 1024); } while (0)
; #define PG8_MMA(ai, bj, At, Bt) do { __builtin_amdgcn_s_setprio(1); _Pragma("unroll") for (int m = 0; m < 4; ++m) _Pragma("unroll") for (int n = 0; n < 2; ++n) _Pragma("unroll") for (int k = 0; k < 2; ++k) \
;         acc[ai][bj][m][n] = __builtin_amdgcn_mfma_f32_16x16x32_bf16(Bt[n][k], At[m][k], acc[ai][bj][m][n], 0, 0, 0); __builtin_amdgcn_s_setprio(0); } while (0)
; #define PG8_WAIT_V(n) asm volatile("s_waitcnt vmcnt(" #n ")" ::: "memory")
; #define PG8_WAIT_L(n) asm volatile("s_waitcnt lgkmcnt(" #n ")" ::: "memory")
; #define PG8_BAR __builtin_amdgcn_s_barrier()
; #define PG8_SCHED __builtin_amdgcn_sched_barrier(0)
; template <class Epi, class Sched>
; __device__ __forceinline__ void gemm_phase(LAS unsigned char* lds, const Gemm g, const Sched& S, const Epi& E) {
;     ...
;             PG8_LDA(At, 1, 1); PG8_STAGE(PG8_SB(1, 0), b3, voffB); PG8_STAGE(PG8_SB(1, 1), b3 + hstepB, voffB); PG8_STAGE(PG8_SA(1, 0), a3, voffA);
;             PG8_WAIT_V(8); PG8_WAIT_L(0); PG8_BAR; PG8_MMA(1, 0, At, B0); PG8_MMA(1, 1, At, B1); PG8_BAR; PG8_SCHED;
;         }
;         if (wr == 0) PG8_BAR;
	s_add_i32 s40, s48, s5
	v_lshl_add_u64 v[150:151], v[150:151], 0, s[10:11]
	s_mov_b32 m0, s40
	ds_read_b128 v[188:191], v157 offset:49152
	ds_read_b128 v[192:195], v157 offset:50176
	ds_read_b128 v[196:199], v157 offset:51200
	ds_read_b128 v[200:203], v157 offset:52224
	ds_read_b128 v[204:207], v157 offset:53248
	ds_read_b128 v[208:211], v157 offset:54272
	ds_read_b128 v[212:215], v157 offset:55296
	ds_read_b128 v[216:219], v157 offset:56320
	global_load_lds_dwordx4 v[150:151], off
	s_add_i32 m0, s40, 0x2000
	s_add_u32 s38, s38, 0x80080
	v_lshl_add_u64 v[150:151], v[220:221], 0, s[10:11]
	s_addc_u32 s39, s39, 0
	s_add_i32 s40, s49, s5
	global_load_lds_dwordx4 v[150:151], off
	v_lshl_add_u64 v[150:151], s[38:39], 0, v[130:131]
	s_mov_b32 m0, s40
	s_nop 0
	global_load_lds_dwordx4 v[150:151], off
	v_lshl_add_u64 v[150:151], s[38:39], 0, v[134:135]
	s_add_i32 m0, s40, 0x2000
	s_nop 0
	global_load_lds_dwordx4 v[150:151], off
	v_lshl_add_u64 v[150:151], v[222:223], 0, s[98:99]
	s_mov_b32 m0, s43
	s_nop 0
	global_load_lds_dwordx4 v[150:151], off
	v_lshl_add_u64 v[150:151], v[224:225], 0, s[98:99]
	s_mov_b32 m0, s44
	s_nop 0
	global_load_lds_dwordx4 v[150:151], off
	s_waitcnt vmcnt(8)
	s_waitcnt lgkmcnt(0)
	s_barrier
	s_waitcnt lgkmcnt(0)
	v_mfma_f32_16x16x32_bf16 v[60:63], v[146:149], v[188:191], v[60:63]
	v_mfma_f32_16x16x32_bf16 v[56:59], v[164:167], v[188:191], v[56:59]
	v_mfma_f32_16x16x32_bf16 v[44:47], v[146:149], v[196:199], v[44:47]
	v_mfma_f32_16x16x32_bf16 v[40:43], v[164:167], v[196:199], v[40:43]
	v_mfma_f32_16x16x32_bf16 v[28:31], v[146:149], v[204:207], v[28:31]
	v_mfma_f32_16x16x32_bf16 v[24:27], v[164:167], v[204:207], v[24:27]
	v_mfma_f32_16x16x32_bf16 v[12:15], v[146:149], v[212:215], v[12:15]
	v_mfma_f32_16x16x32_bf16 v[8:11], v[164:167], v[212:215], v[8:11]
	v_mfma_f32_16x16x32_bf16 v[60:63], v[160:163], v[192:195], v[60:63]
	v_mfma_f32_16x16x32_bf16 v[56:59], v[168:171], v[192:195], v[56:59]
	v_mfma_f32_16x16x32_bf16 v[44:47], v[160:163], v[200:203], v[44:47]
	v_mfma_f32_16x16x32_bf16 v[40:43], v[168:171], v[200:203], v[40:43]
	v_mfma_f32_16x16x32_bf16 v[28:31], v[160:163], v[208:211], v[28:31]
	v_mfma_f32_16x16x32_bf16 v[24:27], v[168:171], v[208:211], v[24:27]
	v_mfma_f32_16x16x32_bf16 v[12:15], v[160:163], v[216:219], v[12:15]
	v_mfma_f32_16x16x32_bf16 v[8:11], v[168:171], v[216:219], v[8:11]
	v_mfma_f32_16x16x32_bf16 v[52:55], v[172:175], v[188:191], v[52:55]
	v_mfma_f32_16x16x32_bf16 v[48:51], v[180:183], v[188:191], v[48:51]
	v_mfma_f32_16x16x32_bf16 v[36:39], v[172:175], v[196:199], v[36:39]
	v_mfma_f32_16x16x32_bf16 v[32:35], v[180:183], v[196:199], v[32:35]
	v_mfma_f32_16x16x32_bf16 v[20:23], v[172:175], v[204:207], v[20:23]
	v_mfma_f32_16x16x32_bf16 v[16:19], v[180:183], v[204:207], v[16:19]
	v_mfma_f32_16x16x32_bf16 v[4:7], v[172:175], v[212:215], v[4:7]
	v_mfma_f32_16x16x32_bf16 v[0:3], v[180:183], v[212:215], v[0:3]
	v_mfma_f32_16x16x32_bf16 v[52:55], v[176:179], v[192:195], v[52:55]
	v_mfma_f32_16x16x32_bf16 v[48:51], v[184:187], v[192:195], v[48:51]
	v_mfma_f32_16x16x32_bf16 v[36:39], v[176:179], v[200:203], v[36:39]
	v_mfma_f32_16x16x32_bf16 v[32:35], v[184:187], v[200:203], v[32:35]
	v_mfma_f32_16x16x32_bf16 v[20:23], v[176:179], v[208:211], v[20:23]
	v_mfma_f32_16x16x32_bf16 v[16:19], v[184:187], v[208:211], v[16:19]
	v_mfma_f32_16x16x32_bf16 v[4:7], v[176:179], v[216:219], v[4:7]
	v_mfma_f32_16x16x32_bf16 v[0:3], v[184:187], v[216:219], v[0:3]
	s_barrier
	s_add_i32 s55, s55, 2
	s_add_u32 s36, s36, 0x1000
	s_addc_u32 s37, s37, 0
	s_add_u32 s53, s53, 0x100
	s_addc_u32 s54, s54, 0
	s_cmp_gt_u32 s55, 29
	s_cbranch_scc0 .LBB0_837
	s_setprio 0
	s_and_b64 vcc, exec, s[12:13]
	s_cbranch_vccz .LBB0_840
	s_barrier
